# speedup vs baseline: 1.0161x; 1.0030x over previous
.LBB0_1346:
	s_mov_b64 s[0:1], 0
	s_waitcnt lgkmcnt(0)
	s_barrier

.LBB0_1784:
	s_or_b64 exec, exec, s[0:1]
	s_add_i32 s12, s12, s77
	s_cmpk_gt_i32 s12, 0x1ff
	s_cselect_b64 s[0:1], -1, 0
	s_waitcnt lgkmcnt(0)
	s_barrier
